# P3 prologue: loads of the 2nd/3rd earlier-segment state iterations also issued once ahead of the loop into unused registers (L2 warm-up), otherwise as previous version
# baseline (speedup 1.0000x reference)
.LBB0_750:
	s_lshr_b32 s11, s48, 7
	v_and_b32_e32 v70, 31, v128
	v_lshrrev_b32_e32 v47, 5, v2
	v_mov_b32_e32 v15, 0
	s_andn2_b64 vcc, exec, s[0:1]
	v_mov_b32_e32 v14, 0
	v_mov_b32_e32 v13, 0
	v_mov_b32_e32 v12, 0
	v_mov_b32_e32 v11, 0
	v_mov_b32_e32 v10, 0
	v_mov_b32_e32 v9, 0
	v_mov_b32_e32 v8, 0
	v_mov_b32_e32 v7, 0
	v_mov_b32_e32 v6, 0
	v_mov_b32_e32 v5, 0
	v_mov_b32_e32 v4, 0
	v_mov_b32_e32 v3, 0
	v_mov_b32_e32 v2, 0
	v_mov_b32_e32 v1, 0
	v_mov_b32_e32 v0, 0
	s_waitcnt vmcnt(16)
	v_mov_b32_e32 v31, 0
	v_mov_b32_e32 v30, 0
	v_mov_b32_e32 v29, 0
	v_mov_b32_e32 v28, 0
	s_waitcnt vmcnt(8)
	v_mov_b32_e32 v27, 0
	v_mov_b32_e32 v26, 0
	v_mov_b32_e32 v25, 0
	v_mov_b32_e32 v24, 0
	s_waitcnt vmcnt(4)
	v_mov_b32_e32 v23, 0
	v_mov_b32_e32 v22, 0
	v_mov_b32_e32 v21, 0
	v_mov_b32_e32 v20, 0
	v_mov_b32_e32 v19, 0
	v_mov_b32_e32 v18, 0
	v_mov_b32_e32 v33, 0
	v_mov_b32_e32 v16, 0
	s_cbranch_vccnz .LBB0_756
	v_lshlrev_b32_e32 v0, 9, v47
	s_lshl_b32 s61, s10, 6
	v_lshl_or_b32 v0, s11, 12, v0
	s_add_i32 s0, 0, 0x20e00
	v_mov_b32_e32 v33, 0
	s_and_b32 s6, s22, 63
	v_mov_b32_e32 v1, 0x600
	v_or3_b32 v0, v0, s61, v70
	v_add_u32_e32 v71, s0, v32
	v_mad_u64_u32 v[16:17], s[0:1], s6, v1, v[32:33]
	v_ashrrev_i32_e32 v1, 31, v0
	v_lshlrev_b64 v[0:1], 2, v[0:1]
	v_mov_b32_e32 v2, 0x30000
	v_mad_u64_u32 v[34:35], s[0:1], s6, v2, v[0:1]
	v_or_b32_e32 v16, 0x9f00000, v16
	s_add_i32 s12, 0, 0x214e0
	s_mov_b32 s13, 0x9300000
	s_mov_b32 s14, 0x9301000
	s_mov_b32 s15, 0x9302000
	s_mov_b32 s16, 0x9303000
	s_mov_b64 s[0:1], 0x200
	s_mov_b64 s[6:7], 0x10000
	s_mov_b32 s17, s20
	v_mov_b32_e32 v32, v33
	v_mov_b32_e32 v18, v33
	v_mov_b32_e32 v19, v33
	v_mov_b32_e32 v20, v33
	v_mov_b32_e32 v21, v33
	v_mov_b32_e32 v22, v33
	v_mov_b32_e32 v23, v33
	v_mov_b32_e32 v24, v33
	v_mov_b32_e32 v25, v33
	v_mov_b32_e32 v26, v33
	v_mov_b32_e32 v27, v33
	v_mov_b32_e32 v28, v33
	v_mov_b32_e32 v29, v33
	v_mov_b32_e32 v30, v33
	v_mov_b32_e32 v31, v33
	v_mov_b32_e32 v0, v33
	v_mov_b32_e32 v1, v33
	v_mov_b32_e32 v2, v33
	v_mov_b32_e32 v3, v33
	v_mov_b32_e32 v4, v33
	v_mov_b32_e32 v5, v33
	v_mov_b32_e32 v6, v33
	v_mov_b32_e32 v7, v33
	v_mov_b32_e32 v8, v33
	v_mov_b32_e32 v9, v33
	v_mov_b32_e32 v10, v33
	v_mov_b32_e32 v11, v33
	v_mov_b32_e32 v12, v33
	v_mov_b32_e32 v13, v33
	v_mov_b32_e32 v14, v33
	v_mov_b32_e32 v15, v33
	s_cmp_lt_u32 s17, 2
	s_cbranch_scc1 .Lp3_segtouch_done
	v_lshl_add_u64 v[134:135], v[34:35], 0, s[6:7]
	v_lshl_add_u64 v[136:137], s[28:29], 0, v[134:135]
	v_add_co_u32_e32 v140, vcc, s13, v136
	s_nop 0
	v_addc_co_u32_e32 v141, vcc, 0, v137, vcc
	v_add_co_u32_e32 v152, vcc, s14, v136
	s_nop 1
	v_addc_co_u32_e32 v153, vcc, 0, v137, vcc
	v_add_co_u32_e32 v154, vcc, s15, v136
	s_nop 1
	v_addc_co_u32_e32 v155, vcc, 0, v137, vcc
	v_add_co_u32_e32 v172, vcc, s16, v136
	s_nop 1
	v_addc_co_u32_e32 v173, vcc, 0, v137, vcc
	global_load_dword v149, v[140:141], off offset:512
	global_load_dword v150, v[140:141], off offset:1024
	global_load_dword v151, v[140:141], off offset:1536
	global_load_dword v137, v[140:141], off offset:1664
	global_load_dword v142, v[154:155], off offset:128
	global_load_dword v136, v[140:141], off offset:1152
	global_load_dword v139, v[140:141], off offset:640
	global_load_dword v138, v[140:141], off offset:128
	global_load_dword v159, v[152:153], off offset:512
	global_load_dword v160, v[152:153], off offset:1024
	global_load_dword v161, v[152:153], off offset:1536
	global_load_dword v162, v[172:173], off offset:-4096
	global_load_dword v145, v[152:153], off offset:1664
	global_load_dword v144, v[152:153], off offset:1152
	global_load_dword v141, v[152:153], off offset:640
	global_load_dword v140, v[152:153], off offset:128
	global_load_dword v148, v[152:153], off offset:-4096
	global_load_dword v158, v[152:153], off
	global_load_dword v163, v[154:155], off offset:512
	global_load_dword v164, v[154:155], off offset:1024
	global_load_dword v165, v[154:155], off offset:1536
	s_nop 0
	global_load_dword v153, v[154:155], off offset:1664
	global_load_dword v152, v[154:155], off offset:1152
	global_load_dword v143, v[154:155], off offset:640
	global_load_dword v166, v[172:173], off
	global_load_dword v167, v[172:173], off offset:512
	global_load_dword v168, v[172:173], off offset:1024
	global_load_dword v169, v[172:173], off offset:1536
	global_load_dword v157, v[172:173], off offset:1664
	global_load_dword v156, v[172:173], off offset:1152
	global_load_dword v155, v[172:173], off offset:640
	global_load_dword v154, v[172:173], off offset:128
	s_cmp_lt_u32 s17, 3
	s_cbranch_scc1 .Lp3_segtouch_done
	v_lshl_add_u64 v[174:175], v[134:135], 0, s[6:7]
	v_lshl_add_u64 v[176:177], s[28:29], 0, v[174:175]
	v_add_co_u32_e32 v180, vcc, s13, v176
	s_nop 0
	v_addc_co_u32_e32 v181, vcc, 0, v177, vcc
	v_add_co_u32_e32 v192, vcc, s14, v176
	s_nop 1
	v_addc_co_u32_e32 v193, vcc, 0, v177, vcc
	v_add_co_u32_e32 v194, vcc, s15, v176
	s_nop 1
	v_addc_co_u32_e32 v195, vcc, 0, v177, vcc
	v_add_co_u32_e32 v212, vcc, s16, v176
	s_nop 1
	v_addc_co_u32_e32 v213, vcc, 0, v177, vcc
	global_load_dword v189, v[180:181], off offset:512
	global_load_dword v190, v[180:181], off offset:1024
	global_load_dword v191, v[180:181], off offset:1536
	global_load_dword v177, v[180:181], off offset:1664
	global_load_dword v182, v[194:195], off offset:128
	global_load_dword v176, v[180:181], off offset:1152
	global_load_dword v179, v[180:181], off offset:640
	global_load_dword v178, v[180:181], off offset:128
	global_load_dword v199, v[192:193], off offset:512
	global_load_dword v200, v[192:193], off offset:1024
	global_load_dword v201, v[192:193], off offset:1536
	global_load_dword v202, v[212:213], off offset:-4096
	global_load_dword v185, v[192:193], off offset:1664
	global_load_dword v184, v[192:193], off offset:1152
	global_load_dword v181, v[192:193], off offset:640
	global_load_dword v180, v[192:193], off offset:128
	global_load_dword v188, v[192:193], off offset:-4096
	global_load_dword v198, v[192:193], off
	global_load_dword v203, v[194:195], off offset:512
	global_load_dword v204, v[194:195], off offset:1024
	global_load_dword v205, v[194:195], off offset:1536
	s_nop 0
	global_load_dword v193, v[194:195], off offset:1664
	global_load_dword v192, v[194:195], off offset:1152
	global_load_dword v183, v[194:195], off offset:640
	global_load_dword v206, v[212:213], off
	global_load_dword v207, v[212:213], off offset:512
	global_load_dword v208, v[212:213], off offset:1024
	global_load_dword v209, v[212:213], off offset:1536
	global_load_dword v197, v[212:213], off offset:1664
	global_load_dword v196, v[212:213], off offset:1152
	global_load_dword v195, v[212:213], off offset:640
	global_load_dword v194, v[212:213], off offset:128
.Lp3_segtouch_done:
	s_branch .LBB0_753
